# glr_panels: reload path gets counted vmcnt(23..16) so next fragment set stays in flight
# speedup vs baseline: 1.0132x; 1.0028x over previous
.Lglr0_b:
	s_waitcnt vmcnt(23)
	v_mfma_f32_32x32x16_bf16 v[0:15], v[96:99], v[140:143], v[0:15]
	s_add_i32 s20, s20, 16
	v_lshl_add_u64 v[158:159], v[158:159], 0, s[12:13]
	v_lshl_add_u64 v[160:161], v[160:161], 0, s[12:13]
	s_and_b64 vcc, exec, s[14:15]
	s_waitcnt vmcnt(22)
	v_mfma_f32_32x32x16_bf16 v[0:15], v[92:95], v[136:139], v[0:15]
	s_waitcnt vmcnt(21)
	v_mfma_f32_32x32x16_bf16 v[0:15], v[88:91], v[132:135], v[0:15]
	s_waitcnt vmcnt(20)
	v_mfma_f32_32x32x16_bf16 v[0:15], v[84:87], v[124:127], v[0:15]
	s_waitcnt vmcnt(19)
	v_mfma_f32_32x32x16_bf16 v[0:15], v[112:115], v[128:131], v[0:15]
	s_waitcnt vmcnt(18)
	v_mfma_f32_32x32x16_bf16 v[0:15], v[108:111], v[120:123], v[0:15]
	s_waitcnt vmcnt(17)
	v_mfma_f32_32x32x16_bf16 v[0:15], v[104:107], v[116:119], v[0:15]
	s_waitcnt vmcnt(16)
	v_mfma_f32_32x32x16_bf16 v[0:15], v[80:83], v[100:103], v[0:15]
	s_cbranch_vccnz .LBB0_243
	s_branch .LBB0_246

.Lglr1_b:
	s_waitcnt vmcnt(29)
	v_mfma_f32_32x32x16_bf16 v[0:15], v[96:99], v[108:111], v[0:15]
	s_add_i32 s20, s20, 16
	v_lshl_add_u64 v[158:159], v[158:159], 0, s[12:13]
	v_lshl_add_u64 v[160:161], v[160:161], 0, s[12:13]
	s_and_b64 vcc, exec, s[14:15]
	s_waitcnt vmcnt(28)
	v_mfma_f32_32x32x16_bf16 v[0:15], v[88:91], v[104:107], v[0:15]
	s_waitcnt vmcnt(25)
	v_mfma_f32_32x32x16_bf16 v[0:15], v[100:103], v[132:135], v[0:15]
	s_waitcnt vmcnt(24)
	v_mfma_f32_32x32x16_bf16 v[0:15], v[92:95], v[124:127], v[0:15]
	s_waitcnt vmcnt(21)
	v_mfma_f32_32x32x16_bf16 v[0:15], v[116:119], v[136:139], v[0:15]
	s_waitcnt vmcnt(20)
	v_mfma_f32_32x32x16_bf16 v[0:15], v[112:115], v[128:131], v[0:15]
	s_waitcnt vmcnt(17)
	v_mfma_f32_32x32x16_bf16 v[0:15], v[120:123], v[140:143], v[0:15]
	s_waitcnt vmcnt(16)
	v_mfma_f32_32x32x16_bf16 v[0:15], v[80:83], v[84:87], v[0:15]
	s_cbranch_vccnz .LBB0_636
	s_branch .LBB0_639
